# MLA loop: back edge rotated (buffer/address bookkeeping before the barrier, next tile's LDS-DMA issued inside the Q.K segment so the segment starts with resident-input MFMAs)
# baseline (speedup 1.0000x reference)
; template <bool MLA> __device__ __forceinline__ void attn_unit(const AttnP& P, int b, int hh, int qb, LAS char* lds) {
;     ...
;     const int qlo = q0 + wid * 32, qm = qlo + r32 - 4 * hi;
;     bf16x8 qr[NQF];
;     const size_t qrow = rowbase + qlo + r32;
;     if constexpr (MLA) {
; #pragma unroll
;         for (int d0 = 0; d0 < 8; ++d0) qr[d0] = *(const bf16x8*)(P.QN + qrow * 2048 + hh * 128 + d0 * 16 + hi * 8);
; #pragma unroll
;         for (int d0 = 0; d0 < 4; ++d0) qr[8 + d0] = *(const bf16x8*)(P.QR + qrow * 1024 + hh * 64 + d0 * 16 + hi * 8);
;     } else {
; #pragma unroll
;         for (int d0 = 0; d0 < 4; ++d0) qr[d0] = *(const bf16x8*)(P.QS + qrow * 2048 + hh * 64 + d0 * 16 + hi * 8);
;         if (tid < 128) bias_l[tid] = P.rel[(int)T5B[tid] * 32 + hh] * (1.0f / SCALE);
;     }
;     bf16x8 sk0, sv0;
;     const int sr8 = tid >> 3, ch8 = tid & 7;
;     const bf16_t* Kg; const bf16_t* Vg; const bf16_t* Rg = nullptr;
;     unsigned okA = 0, okB = 0, orp = 0, ovA = 0, ovB = 0;
;     if constexpr (MLA) {
;         Kg = P.KN + rowbase * 2048 + hh * 128; Vg = P.V + rowbase * 2048 + hh * 128; Rg = P.KR + rowbase * 64;
;         { const int rA = 4 * wid + (lane >> 4), rB = rA + 32, cp = lane & 15; okA = (unsigned)(rA * 2048 + ((cp ^ (rA & 7)) << 3)); okB = (unsigned)(rB * 2048 + ((cp ^ (rB & 7)) << 3)); }
;         { const int rr = 8 * wid + (lane >> 3), cp = lane & 7; orp = (unsigned)(rr * 64 + ((cp ^ (rr & 7)) << 3)); }
;         { const int stA = 2 * wid + (lane >> 5), stB = stA + 16; const int kl = (lane & 31) >> 2, c8 = 8 * (lane & 3);
;           const int kkA = (stA >> 2) * 8 + kl, kkB = (stB >> 2) * 8 + kl;
;           const int kA = (kkA & ~0xC) | ((kkA & 4) << 1) | ((kkA & 8) >> 1), kB = (kkB & ~0xC) | ((kkB & 4) << 1) | ((kkB & 8) >> 1);
;           ovA = (unsigned)(kA * 2048 + 32 * (stA & 3) + c8); ovB = (unsigned)(kB * 2048 + 32 * (stB & 3) + c8); }
;     } else { Kg = P.KS + (rowbase + sr8) * 256 + (hh >> 3) * 64 + ch8 * 8; Vg = P.VS + (rowbase + sr8) * 256 + (hh >> 3) * 64 + ch8 * 8; }
;     const int kws = KSWZ64(sr8, ch8), vst0 = v_st<NCB>(sr8, ch8 * 8);
;     ...
;     float m_reg = MLA ? 0.f : P.sinks[hh] * (1.0f / SCALE), l_reg = MLA ? 0.f : 1.f;
;     f32x16 o[NCB];
; #pragma unroll
;     for (int d = 0; d < NCB; ++d) o[d] = f32x16{};
;     const int vb0 = (int)(uintptr_t)V_lds + v_rd_base(lane);
.Lm16_qb_ok:
	s_lshr_b32 s36, s28, 5
	s_and_b32 s63, s36, 15
	s_lshr_b32 s64, s36, 4
	s_lshl_b32 s40, s33, 2
	s_add_u32 s40, s40, 4
	s_lshl_b32 s43, s33, 8
	s_lshl_b32 s36, s4, 5
	s_add_u32 s43, s43, s36
	s_lshl_b32 s36, s64, 14
	s_add_u32 s36, s36, s43
	s_lshl_b32 s37, s36, 12
	s_lshl_b32 s59, s63, 8
	s_add_u32 s37, s37, s59
	s_add_u32 s66, s6, s37
	s_addc_u32 s67, s7, 0
	s_lshl_b32 s37, s36, 11
	s_lshl_b32 s59, s63, 7
	s_add_u32 s37, s37, s59
	s_add_u32 s68, s8, s37
	s_addc_u32 s69, s9, 0
	s_lshl_b32 s37, s64, 26
	s_lshl_b32 s59, s63, 8
	s_add_u32 s37, s37, s59
	s_add_u32 s46, s12, s37
	s_addc_u32 s47, s13, 0
	s_add_u32 s48, s16, s37
	s_addc_u32 s49, s17, 0
	s_lshl_b32 s37, s64, 21
	s_add_u32 s50, s14, s37
	s_addc_u32 s51, s15, 0
	global_load_dwordx4 v[66:69], v237, s[66:67] offset:0
	global_load_dwordx4 v[70:73], v237, s[66:67] offset:64
	global_load_dwordx4 v[74:77], v237, s[66:67] offset:128
	global_load_dwordx4 v[78:81], v237, s[66:67] offset:192
	global_load_dwordx4 v[82:85], v239, s[68:69] offset:0
	global_load_dwordx4 v[86:89], v239, s[68:69] offset:64
	global_load_dwordx4 v[90:93], v238, s[66:67] offset:0
	global_load_dwordx4 v[94:97], v238, s[66:67] offset:64
	global_load_dwordx4 v[98:101], v238, s[66:67] offset:128
	global_load_dwordx4 v[102:105], v238, s[66:67] offset:192
	global_load_dwordx4 v[106:109], v240, s[68:69] offset:0
	global_load_dwordx4 v[110:113], v240, s[68:69] offset:64
	s_mov_b32 s70, 0x8000
	s_mov_b32 s71, 0
	s_add_i32 s36, s5, s70
	s_mov_b32 m0, s36
	s_nop 0
	global_load_lds_dwordx4 v232, s[46:47]
	s_add_i32 m0, s36, 0x2000
	s_nop 0
	global_load_lds_dwordx4 v233, s[46:47]
	s_add_i32 m0, s36, 0x4000
	s_nop 0
	global_load_lds_dwordx4 v234, s[50:51]
	s_add_i32 s36, s5, s71
	s_mov_b32 m0, s36
	s_nop 0
	global_load_lds_dwordx4 v235, s[48:49]
	s_add_i32 m0, s36, 0x2000
	s_nop 0
	global_load_lds_dwordx4 v236, s[48:49]
	s_add_u32 s46, s46, 0x40000
	s_addc_u32 s47, s47, 0
	s_add_u32 s48, s48, 0x40000
	s_addc_u32 s49, s49, 0
	s_add_u32 s50, s50, 0x2000
	s_addc_u32 s51, s51, 0
	v_mov_b32_e32 v2, 0
	v_mov_b32_e32 v3, 0
	v_mov_b32_e32 v4, 0
	v_mov_b32_e32 v5, 0
	v_mov_b32_e32 v6, 0
	v_mov_b32_e32 v7, 0
	v_mov_b32_e32 v8, 0
	v_mov_b32_e32 v9, 0
	v_mov_b32_e32 v10, 0
	v_mov_b32_e32 v11, 0
	v_mov_b32_e32 v12, 0
	v_mov_b32_e32 v13, 0
	v_mov_b32_e32 v14, 0
	v_mov_b32_e32 v15, 0
	v_mov_b32_e32 v16, 0
	v_mov_b32_e32 v17, 0
	v_mov_b32_e32 v18, 0
	v_mov_b32_e32 v19, 0
	v_mov_b32_e32 v20, 0
	v_mov_b32_e32 v21, 0
	v_mov_b32_e32 v22, 0
	v_mov_b32_e32 v23, 0
	v_mov_b32_e32 v24, 0
	v_mov_b32_e32 v25, 0
	v_mov_b32_e32 v26, 0
	v_mov_b32_e32 v27, 0
	v_mov_b32_e32 v28, 0
	v_mov_b32_e32 v29, 0
	v_mov_b32_e32 v30, 0
	v_mov_b32_e32 v31, 0
	v_mov_b32_e32 v32, 0
	v_mov_b32_e32 v33, 0
	v_mov_b32_e32 v34, 0
	v_mov_b32_e32 v35, 0
	v_mov_b32_e32 v36, 0
	v_mov_b32_e32 v37, 0
	v_mov_b32_e32 v38, 0
	v_mov_b32_e32 v39, 0
	v_mov_b32_e32 v40, 0
	v_mov_b32_e32 v41, 0
	v_mov_b32_e32 v42, 0
	v_mov_b32_e32 v43, 0
	v_mov_b32_e32 v44, 0
	v_mov_b32_e32 v45, 0
	v_mov_b32_e32 v46, 0
	v_mov_b32_e32 v47, 0
	v_mov_b32_e32 v48, 0
	v_mov_b32_e32 v49, 0
	v_mov_b32_e32 v50, 0
	v_mov_b32_e32 v51, 0
	v_mov_b32_e32 v52, 0
	v_mov_b32_e32 v53, 0
	v_mov_b32_e32 v54, 0
	v_mov_b32_e32 v55, 0
	v_mov_b32_e32 v56, 0
	v_mov_b32_e32 v57, 0
	v_mov_b32_e32 v58, 0
	v_mov_b32_e32 v59, 0
	v_mov_b32_e32 v60, 0
	v_mov_b32_e32 v61, 0
	v_mov_b32_e32 v62, 0
	v_mov_b32_e32 v63, 0
	v_mov_b32_e32 v64, 0
	v_mov_b32_e32 v65, 0
	v_mov_b32_e32 v216, 0
	v_mov_b32_e32 v218, 0
	v_mov_b32_e32 v208, 0
	v_mov_b32_e32 v209, 0
	v_mov_b32_e32 v210, 0
	v_mov_b32_e32 v211, 0
	v_mov_b32_e32 v217, 0
	v_mov_b32_e32 v219, 0
	v_mov_b32_e32 v212, 0
	v_mov_b32_e32 v213, 0
	v_mov_b32_e32 v214, 0
	v_mov_b32_e32 v215, 0
	s_mov_b32 s41, 0
	s_mov_b32 s42, 0
	s_mov_b32 s74, 0xe000
	s_mov_b32 s75, 0x4000
	v_add_u32_e32 v228, s70, v224
	v_add_u32_e32 v229, s70, v225
	v_add_u32_e32 v230, s71, v226
	v_add_u32_e32 v231, s71, v227
	s_waitcnt vmcnt(0)
	s_barrier
.Lm16_tile:
	s_add_u32 s36, s43, 31
	s_cmp_gt_u32 s42, s36
	s_cbranch_scc1 .Lm16_inact
	ds_read_b128 v[180:183], v228 offset:0
	ds_read_b128 v[184:187], v228 offset:2048
	ds_read_b128 v[188:191], v228 offset:4096
	ds_read_b128 v[192:195], v228 offset:6144
	s_waitcnt lgkmcnt(3)
	v_mfma_f32_16x16x32_bf16 v[114:117], v[180:183], v[66:69], v[208:211]
	v_mfma_f32_16x16x32_bf16 v[118:121], v[180:183], v[90:93], v[212:215]
	ds_read_b128 v[180:183], v229 offset:0
	s_waitcnt lgkmcnt(3)
	v_mfma_f32_16x16x32_bf16 v[122:125], v[184:187], v[66:69], v[208:211]
	v_mfma_f32_16x16x32_bf16 v[126:129], v[184:187], v[90:93], v[212:215]
	ds_read_b128 v[184:187], v229 offset:2048
	s_waitcnt lgkmcnt(3)
	v_mfma_f32_16x16x32_bf16 v[130:133], v[188:191], v[66:69], v[208:211]
	v_mfma_f32_16x16x32_bf16 v[134:137], v[188:191], v[90:93], v[212:215]
	ds_read_b128 v[188:191], v229 offset:4096
	s_waitcnt lgkmcnt(3)
	v_mfma_f32_16x16x32_bf16 v[138:141], v[192:195], v[66:69], v[208:211]
	v_mfma_f32_16x16x32_bf16 v[142:145], v[192:195], v[90:93], v[212:215]
	s_add_u32 s36, s41, 1
	s_cmp_lt_u32 s36, s40
	s_cbranch_scc0 .Lm16_nold
	s_add_i32 s36, s5, s74
	s_mov_b32 m0, s36
	s_nop 0
	global_load_lds_dwordx4 v232, s[46:47]
	s_add_i32 m0, s36, 0x2000
	s_nop 0
	global_load_lds_dwordx4 v233, s[46:47]
	s_add_i32 m0, s36, 0x4000
	s_nop 0
	global_load_lds_dwordx4 v234, s[50:51]
	s_add_i32 s36, s5, s75
	s_mov_b32 m0, s36
	s_nop 0
	global_load_lds_dwordx4 v235, s[48:49]
	s_add_i32 m0, s36, 0x2000
	s_nop 0
	global_load_lds_dwordx4 v236, s[48:49]
	s_add_u32 s46, s46, 0x40000
	s_addc_u32 s47, s47, 0
	s_add_u32 s48, s48, 0x40000
	s_addc_u32 s49, s49, 0
	s_add_u32 s50, s50, 0x2000
	s_addc_u32 s51, s51, 0
; #define WLK(n) do { asm volatile("s_waitcnt lgkmcnt(" #n ")" ::: "memory"); SBAR(); } while (0)
; #define RDN(S, dd, off) do { const int a_ = rb + (((dd) * 32 + h16) ^ sw); KRD(S##0, a_, off); KRD(S##1, a_, 8192 + (off)); } while (0)
; #define RDR(S, ks) do { const int a_ = rr + (((((ks) * 2 + hi)) ^ (r32 & 7)) << 4); KRD(S##0, a_, 0); KRD(S##1, a_, 4096); } while (0)
; #define MM1(S, d) do { p0 = __builtin_amdgcn_mfma_f32_32x32x16_bf16(S##0, qr[d], p0, 0, 0, 0); p1 = __builtin_amdgcn_mfma_f32_32x32x16_bf16(S##1, qr[d], p1, 0, 0, 0); } while (0)
; __device__ __forceinline__ void mask_tile(f32x16& p0, f32x16& p1, int dq, unsigned W) {
;     const float NEG = -__builtin_inff();
; #pragma unroll
;     for (int r = 0; r < 16; ++r) { const int c = (r & 3) + 8 * (r >> 2);
;         if ((unsigned)(dq - c) >= W) p0[r] = NEG;
;         if ((unsigned)(dq - c - 32) >= W) p1[r] = NEG; }
; __device__ __forceinline__ void qk_mla(f32x16& p0, f32x16& p1, int kaddr, int r32, int hi, const bf16x8* qr) {
;     const int rb = kaddr + r32 * 256, sw = (r32 & 7) << 4, h16 = hi * 16;
;     const int rr = kaddr + 16384 + r32 * 128;
;     ...
;     bf16x8 A0, A1, B0, B1;
;     RDN(A, 0, 0); RDN(B, 1, 0);
;     WLK(2); MM1(A, 0); RDN(A, 2, 0);
;     WLK(2); MM1(B, 1); RDN(B, 3, 0);
;     WLK(2); MM1(A, 2); RDN(A, 0, 128);
;     WLK(2); MM1(B, 3); RDN(B, 1, 128);
;     WLK(2); MM1(A, 4); RDN(A, 2, 128);
;     WLK(2); MM1(B, 5); RDN(B, 3, 128);
;     WLK(2); MM1(A, 6); RDR(A, 0);
;     WLK(2); MM1(B, 7); RDR(B, 1);
;     WLK(2); MM1(A, 8); RDR(A, 2);
;     WLK(2); MM1(B, 9); RDR(B, 3);
;     WLK(2); MM1(A, 10);
;     WLK(0); MM1(B, 11);
.Lm16_nold:
	ds_read_b128 v[192:195], v229 offset:6144
	s_waitcnt lgkmcnt(3)
	v_mfma_f32_16x16x32_bf16 v[114:117], v[180:183], v[70:73], v[114:117]
	v_mfma_f32_16x16x32_bf16 v[118:121], v[180:183], v[94:97], v[118:121]
	ds_read_b128 v[180:183], v228 offset:8192
	s_waitcnt lgkmcnt(3)
	v_mfma_f32_16x16x32_bf16 v[122:125], v[184:187], v[70:73], v[122:125]
	v_mfma_f32_16x16x32_bf16 v[126:129], v[184:187], v[94:97], v[126:129]
	ds_read_b128 v[184:187], v228 offset:10240
	s_waitcnt lgkmcnt(3)
	v_mfma_f32_16x16x32_bf16 v[130:133], v[188:191], v[70:73], v[130:133]
	v_mfma_f32_16x16x32_bf16 v[134:137], v[188:191], v[94:97], v[134:137]
	ds_read_b128 v[188:191], v228 offset:12288
	s_waitcnt lgkmcnt(3)
	v_mfma_f32_16x16x32_bf16 v[138:141], v[192:195], v[70:73], v[138:141]
	v_mfma_f32_16x16x32_bf16 v[142:145], v[192:195], v[94:97], v[142:145]
	ds_read_b128 v[192:195], v228 offset:14336
	s_waitcnt lgkmcnt(3)
	v_mfma_f32_16x16x32_bf16 v[114:117], v[180:183], v[74:77], v[114:117]
	v_mfma_f32_16x16x32_bf16 v[118:121], v[180:183], v[98:101], v[118:121]
	ds_read_b128 v[180:183], v229 offset:8192
	s_waitcnt lgkmcnt(3)
	v_mfma_f32_16x16x32_bf16 v[122:125], v[184:187], v[74:77], v[122:125]
	v_mfma_f32_16x16x32_bf16 v[126:129], v[184:187], v[98:101], v[126:129]
	ds_read_b128 v[184:187], v229 offset:10240
	s_waitcnt lgkmcnt(3)
	v_mfma_f32_16x16x32_bf16 v[130:133], v[188:191], v[74:77], v[130:133]
	v_mfma_f32_16x16x32_bf16 v[134:137], v[188:191], v[98:101], v[134:137]
	ds_read_b128 v[188:191], v229 offset:12288
	s_waitcnt lgkmcnt(3)
	v_mfma_f32_16x16x32_bf16 v[138:141], v[192:195], v[74:77], v[138:141]
	v_mfma_f32_16x16x32_bf16 v[142:145], v[192:195], v[98:101], v[142:145]
	ds_read_b128 v[192:195], v229 offset:14336
	s_waitcnt lgkmcnt(3)
	v_mfma_f32_16x16x32_bf16 v[114:117], v[180:183], v[78:81], v[114:117]
	v_mfma_f32_16x16x32_bf16 v[118:121], v[180:183], v[102:105], v[118:121]
	ds_read_b128 v[180:183], v228 offset:16384
	s_waitcnt lgkmcnt(3)
	v_mfma_f32_16x16x32_bf16 v[122:125], v[184:187], v[78:81], v[122:125]
	v_mfma_f32_16x16x32_bf16 v[126:129], v[184:187], v[102:105], v[126:129]
	ds_read_b128 v[184:187], v228 offset:18432
	s_waitcnt lgkmcnt(3)
	v_mfma_f32_16x16x32_bf16 v[130:133], v[188:191], v[78:81], v[130:133]
	v_mfma_f32_16x16x32_bf16 v[134:137], v[188:191], v[102:105], v[134:137]
	ds_read_b128 v[188:191], v228 offset:20480
	s_waitcnt lgkmcnt(3)
	v_mfma_f32_16x16x32_bf16 v[138:141], v[192:195], v[78:81], v[138:141]
	v_mfma_f32_16x16x32_bf16 v[142:145], v[192:195], v[102:105], v[142:145]
	ds_read_b128 v[192:195], v228 offset:22528
	s_waitcnt lgkmcnt(3)
	v_mfma_f32_16x16x32_bf16 v[114:117], v[180:183], v[82:85], v[114:117]
	v_mfma_f32_16x16x32_bf16 v[118:121], v[180:183], v[106:109], v[118:121]
	ds_read_b128 v[180:183], v229 offset:16384
	s_waitcnt lgkmcnt(3)
	v_mfma_f32_16x16x32_bf16 v[122:125], v[184:187], v[82:85], v[122:125]
	v_mfma_f32_16x16x32_bf16 v[126:129], v[184:187], v[106:109], v[126:129]
	ds_read_b128 v[184:187], v229 offset:18432
	s_waitcnt lgkmcnt(3)
	v_mfma_f32_16x16x32_bf16 v[130:133], v[188:191], v[82:85], v[130:133]
	v_mfma_f32_16x16x32_bf16 v[134:137], v[188:191], v[106:109], v[134:137]
	ds_read_b128 v[188:191], v229 offset:20480
	s_waitcnt lgkmcnt(3)
	v_mfma_f32_16x16x32_bf16 v[138:141], v[192:195], v[82:85], v[138:141]
	v_mfma_f32_16x16x32_bf16 v[142:145], v[192:195], v[106:109], v[142:145]
	ds_read_b128 v[192:195], v229 offset:22528
	s_waitcnt lgkmcnt(3)
	v_mfma_f32_16x16x32_bf16 v[114:117], v[180:183], v[86:89], v[114:117]
	v_mfma_f32_16x16x32_bf16 v[118:121], v[180:183], v[110:113], v[118:121]
	s_waitcnt lgkmcnt(2)
	v_mfma_f32_16x16x32_bf16 v[122:125], v[184:187], v[86:89], v[122:125]
	v_mfma_f32_16x16x32_bf16 v[126:129], v[184:187], v[110:113], v[126:129]
	s_waitcnt lgkmcnt(1)
	v_mfma_f32_16x16x32_bf16 v[130:133], v[188:191], v[86:89], v[130:133]
	v_mfma_f32_16x16x32_bf16 v[134:137], v[188:191], v[110:113], v[134:137]
	s_waitcnt lgkmcnt(0)
	v_mfma_f32_16x16x32_bf16 v[138:141], v[192:195], v[86:89], v[138:141]
	v_mfma_f32_16x16x32_bf16 v[142:145], v[192:195], v[110:113], v[142:145]
	v_add_u32_e32 v228, s74, v224
	v_add_u32_e32 v229, s74, v225
	s_nop 7
	s_add_u32 s36, s42, 63
	s_cmp_gt_u32 s36, s43
	s_cbranch_scc0 .Lm16_nomask
	s_sub_u32 s36, s43, s42
	v_add_u32_e32 v244, s36, v243
	v_cmp_gt_i32_e32 vcc, 0, v244
	s_nop 1
	v_cndmask_b32_e32 v114, v114, v245, vcc
	v_cmp_gt_i32_e32 vcc, 1, v244
	s_nop 1
	v_cndmask_b32_e32 v115, v115, v245, vcc
	v_cmp_gt_i32_e32 vcc, 2, v244
	s_nop 1
	v_cndmask_b32_e32 v116, v116, v245, vcc
	v_cmp_gt_i32_e32 vcc, 3, v244
	s_nop 1
	v_cndmask_b32_e32 v117, v117, v245, vcc
	v_cmp_gt_i32_e32 vcc, -16, v244
	s_nop 1
	v_cndmask_b32_e32 v118, v118, v245, vcc
	v_cmp_gt_i32_e32 vcc, -15, v244
	s_nop 1
	v_cndmask_b32_e32 v119, v119, v245, vcc
	v_cmp_gt_i32_e32 vcc, -14, v244
	s_nop 1
	v_cndmask_b32_e32 v120, v120, v245, vcc
	v_cmp_gt_i32_e32 vcc, -13, v244
	s_nop 1
	v_cndmask_b32_e32 v121, v121, v245, vcc
	v_cmp_gt_i32_e32 vcc, 16, v244
	s_nop 1
	v_cndmask_b32_e32 v122, v122, v245, vcc
	v_cmp_gt_i32_e32 vcc, 17, v244
	s_nop 1
	v_cndmask_b32_e32 v123, v123, v245, vcc
	v_cmp_gt_i32_e32 vcc, 18, v244
	s_nop 1
	v_cndmask_b32_e32 v124, v124, v245, vcc
	v_cmp_gt_i32_e32 vcc, 19, v244
	s_nop 1
	v_cndmask_b32_e32 v125, v125, v245, vcc
	v_cmp_gt_i32_e32 vcc, 0, v244
	s_nop 1
	v_cndmask_b32_e32 v126, v126, v245, vcc
	v_cmp_gt_i32_e32 vcc, 1, v244
	s_nop 1
	v_cndmask_b32_e32 v127, v127, v245, vcc
	v_cmp_gt_i32_e32 vcc, 2, v244
	s_nop 1
	v_cndmask_b32_e32 v128, v128, v245, vcc
	v_cmp_gt_i32_e32 vcc, 3, v244
	s_nop 1
	v_cndmask_b32_e32 v129, v129, v245, vcc
	v_cmp_gt_i32_e32 vcc, 32, v244
	s_nop 1
	v_cndmask_b32_e32 v130, v130, v245, vcc
	v_cmp_gt_i32_e32 vcc, 33, v244
	s_nop 1
	v_cndmask_b32_e32 v131, v131, v245, vcc
	v_cmp_gt_i32_e32 vcc, 34, v244
	s_nop 1
	v_cndmask_b32_e32 v132, v132, v245, vcc
	v_cmp_gt_i32_e32 vcc, 35, v244
	s_nop 1
	v_cndmask_b32_e32 v133, v133, v245, vcc
	v_cmp_gt_i32_e32 vcc, 16, v244
	s_nop 1
	v_cndmask_b32_e32 v134, v134, v245, vcc
	v_cmp_gt_i32_e32 vcc, 17, v244
	s_nop 1
	v_cndmask_b32_e32 v135, v135, v245, vcc
	v_cmp_gt_i32_e32 vcc, 18, v244
	s_nop 1
	v_cndmask_b32_e32 v136, v136, v245, vcc
	v_cmp_gt_i32_e32 vcc, 19, v244
	s_nop 1
	v_cndmask_b32_e32 v137, v137, v245, vcc
	v_cmp_gt_i32_e32 vcc, 48, v244
	s_nop 1
	v_cndmask_b32_e32 v138, v138, v245, vcc
	v_cmp_gt_i32_e32 vcc, 49, v244
	s_nop 1
	v_cndmask_b32_e32 v139, v139, v245, vcc
	v_cmp_gt_i32_e32 vcc, 50, v244
	s_nop 1
	v_cndmask_b32_e32 v140, v140, v245, vcc
	v_cmp_gt_i32_e32 vcc, 51, v244
	s_nop 1
	v_cndmask_b32_e32 v141, v141, v245, vcc
	v_cmp_gt_i32_e32 vcc, 32, v244
	s_nop 1
	v_cndmask_b32_e32 v142, v142, v245, vcc
	v_cmp_gt_i32_e32 vcc, 33, v244
	s_nop 1
	v_cndmask_b32_e32 v143, v143, v245, vcc
	v_cmp_gt_i32_e32 vcc, 34, v244
	s_nop 1
	v_cndmask_b32_e32 v144, v144, v245, vcc
	v_cmp_gt_i32_e32 vcc, 35, v244
	s_nop 1
	v_cndmask_b32_e32 v145, v145, v245, vcc

; #define PV_RD(S, d0) do { constexpr int b_ = (d0) * 512; TRRD(S##l0, b_); TRRD(S##h0, b_ + KS_ / 2); TRRD(S##l1, b_ + KS_); TRRD(S##h1, b_ + KS_ + KS_ / 2); TRRD(S##l2, b_ + 2 * KS_); TRRD(S##h2, b_ + 2 * KS_ + KS_ / 2); TRRD(S##l3, b_ + 3 * KS_); TRRD(S##h3, b_ + 3 * KS_ + KS_ / 2); } while (0)
; #define WL(n) do { asm volatile("s_waitcnt lgkmcnt(" #n ")" ::: "memory"); SBAR(); } while (0)
; __device__ __forceinline__ void finishSM(f32x16& p0, f32x16& p1, float alpha, float& l_reg, bf16x8& pa0, bf16x8& pa1, bf16x8& pa2, bf16x8& pa3) {
; #pragma unroll
;     for (int r = 0; r < 16; ++r) p1[r] = __builtin_amdgcn_exp2f(p1[r]);
;     float ps = 0;
; #pragma unroll
;     for (int r = 0; r < 16; ++r) ps += p0[r];
; #pragma unroll
;     for (int r = 0; r < 16; ++r) ps += p1[r];
;     { auto rr = __builtin_amdgcn_permlane32_swap(__float_as_uint(ps), __float_as_uint(ps), false, false);
;       ps = __uint_as_float(rr[0]) + __uint_as_float(rr[1]); }
;     l_reg = l_reg * alpha + ps;
; template <int NCB> __device__ __forceinline__ void pv_tile(f32x16* o, int vb, bf16x8 pa0, bf16x8 pa1, bf16x8 pa2, bf16x8 pa3) {
;     ...
;     constexpr int KS_ = NCB * 1024;
;     ...
;     s16x4 Al0, Al1, Al2, Al3, Ah0, Ah1, Ah2, Ah3, Bl0, Bl1, Bl2, Bl3, Bh0, Bh1, Bh2, Bh3;
;     PV_RD(A, 0); PV_RD(B, 1); WL(8); PV_MM(A, 0);
;     if constexpr (NCB == 4) { PV_RD(A, 2); WL(8); PV_MM(B, 1); PV_RD(B, 3); WL(8); PV_MM(A, 2); WL(0); PV_MM(B, 3); }
.Lm16_exp:
	v_exp_f32_e32 v114, v114
	v_exp_f32_e32 v115, v115
	v_exp_f32_e32 v116, v116
	v_exp_f32_e32 v117, v117
	v_exp_f32_e32 v118, v118
	v_exp_f32_e32 v119, v119
	v_exp_f32_e32 v120, v120
	v_exp_f32_e32 v121, v121
	v_exp_f32_e32 v122, v122
	v_exp_f32_e32 v123, v123
	v_exp_f32_e32 v124, v124
	v_exp_f32_e32 v125, v125
	v_exp_f32_e32 v126, v126
	v_exp_f32_e32 v127, v127
	v_exp_f32_e32 v128, v128
	v_exp_f32_e32 v129, v129
	v_exp_f32_e32 v130, v130
	v_exp_f32_e32 v131, v131
	v_exp_f32_e32 v132, v132
	v_exp_f32_e32 v133, v133
	v_exp_f32_e32 v134, v134
	v_exp_f32_e32 v135, v135
	v_exp_f32_e32 v136, v136
	v_exp_f32_e32 v137, v137
	v_exp_f32_e32 v138, v138
	v_exp_f32_e32 v139, v139
	v_exp_f32_e32 v140, v140
	v_exp_f32_e32 v141, v141
	v_exp_f32_e32 v142, v142
	v_exp_f32_e32 v143, v143
	v_exp_f32_e32 v144, v144
	v_exp_f32_e32 v145, v145
	v_add_f32_e32 v216, v216, v114
	v_add_f32_e32 v217, v217, v118
	v_add_f32_e32 v216, v216, v115
	v_add_f32_e32 v217, v217, v119
	v_add_f32_e32 v216, v216, v116
	v_add_f32_e32 v217, v217, v120
	v_add_f32_e32 v216, v216, v117
	v_add_f32_e32 v217, v217, v121
	v_add_f32_e32 v216, v216, v122
	v_add_f32_e32 v217, v217, v126
	v_add_f32_e32 v216, v216, v123
	v_add_f32_e32 v217, v217, v127
	v_add_f32_e32 v216, v216, v124
	v_add_f32_e32 v217, v217, v128
	v_add_f32_e32 v216, v216, v125
	v_add_f32_e32 v217, v217, v129
	v_add_f32_e32 v216, v216, v130
	v_add_f32_e32 v217, v217, v134
	v_add_f32_e32 v216, v216, v131
	v_add_f32_e32 v217, v217, v135
	v_add_f32_e32 v216, v216, v132
	v_add_f32_e32 v217, v217, v136
	v_add_f32_e32 v216, v216, v133
	v_add_f32_e32 v217, v217, v137
	v_add_f32_e32 v216, v216, v138
	v_add_f32_e32 v217, v217, v142
	v_add_f32_e32 v216, v216, v139
	v_add_f32_e32 v217, v217, v143
	v_add_f32_e32 v216, v216, v140
	v_add_f32_e32 v217, v217, v144
	v_add_f32_e32 v216, v216, v141
	v_add_f32_e32 v217, v217, v145
	v_cvt_pk_bf16_f32 v164, v114, v115
	v_cvt_pk_bf16_f32 v165, v116, v117
	v_cvt_pk_bf16_f32 v166, v122, v123
	v_cvt_pk_bf16_f32 v167, v124, v125
	v_cvt_pk_bf16_f32 v168, v130, v131
	v_cvt_pk_bf16_f32 v169, v132, v133
	v_cvt_pk_bf16_f32 v170, v138, v139
	v_cvt_pk_bf16_f32 v171, v140, v141
	v_cvt_pk_bf16_f32 v172, v118, v119
	v_cvt_pk_bf16_f32 v173, v120, v121
	v_cvt_pk_bf16_f32 v174, v126, v127
	v_cvt_pk_bf16_f32 v175, v128, v129
	v_cvt_pk_bf16_f32 v176, v134, v135
	v_cvt_pk_bf16_f32 v177, v136, v137
	v_cvt_pk_bf16_f32 v178, v142, v143
	v_cvt_pk_bf16_f32 v179, v144, v145
	ds_read_b64_tr_b16 v[180:181], v230 offset:0
	ds_read_b64_tr_b16 v[182:183], v230 offset:4096
	ds_read_b64_tr_b16 v[184:185], v230 offset:8192
	ds_read_b64_tr_b16 v[186:187], v230 offset:12288
	ds_read_b64_tr_b16 v[188:189], v231 offset:0
	ds_read_b64_tr_b16 v[190:191], v231 offset:4096
	ds_read_b64_tr_b16 v[192:193], v231 offset:8192
	ds_read_b64_tr_b16 v[194:195], v231 offset:12288
	s_waitcnt lgkmcnt(6)
	v_mfma_f32_16x16x32_bf16 v[2:5], v[180:183], v[164:167], v[2:5]
	v_mfma_f32_16x16x32_bf16 v[6:9], v[180:183], v[172:175], v[6:9]
	ds_read_b64_tr_b16 v[180:181], v230 offset:512
	ds_read_b64_tr_b16 v[182:183], v230 offset:4608
	s_waitcnt lgkmcnt(6)
	v_mfma_f32_16x16x32_bf16 v[2:5], v[184:187], v[168:171], v[2:5]
	v_mfma_f32_16x16x32_bf16 v[6:9], v[184:187], v[176:179], v[6:9]
	ds_read_b64_tr_b16 v[184:185], v230 offset:8704
	ds_read_b64_tr_b16 v[186:187], v230 offset:12800
	s_waitcnt lgkmcnt(6)
	v_mfma_f32_16x16x32_bf16 v[10:13], v[188:191], v[164:167], v[10:13]
	v_mfma_f32_16x16x32_bf16 v[14:17], v[188:191], v[172:175], v[14:17]
	ds_read_b64_tr_b16 v[188:189], v231 offset:512
	ds_read_b64_tr_b16 v[190:191], v231 offset:4608
	s_waitcnt lgkmcnt(6)
	v_mfma_f32_16x16x32_bf16 v[10:13], v[192:195], v[168:171], v[10:13]
	v_mfma_f32_16x16x32_bf16 v[14:17], v[192:195], v[176:179], v[14:17]
	ds_read_b64_tr_b16 v[192:193], v231 offset:8704
	ds_read_b64_tr_b16 v[194:195], v231 offset:12800
	s_waitcnt lgkmcnt(6)
	v_mfma_f32_16x16x32_bf16 v[18:21], v[180:183], v[164:167], v[18:21]
	v_mfma_f32_16x16x32_bf16 v[22:25], v[180:183], v[172:175], v[22:25]
	ds_read_b64_tr_b16 v[180:181], v230 offset:1024
	ds_read_b64_tr_b16 v[182:183], v230 offset:5120
	s_waitcnt lgkmcnt(6)
	v_mfma_f32_16x16x32_bf16 v[18:21], v[184:187], v[168:171], v[18:21]
	v_mfma_f32_16x16x32_bf16 v[22:25], v[184:187], v[176:179], v[22:25]
	ds_read_b64_tr_b16 v[184:185], v230 offset:9216
	ds_read_b64_tr_b16 v[186:187], v230 offset:13312
	s_waitcnt lgkmcnt(6)
	v_mfma_f32_16x16x32_bf16 v[26:29], v[188:191], v[164:167], v[26:29]
	v_mfma_f32_16x16x32_bf16 v[30:33], v[188:191], v[172:175], v[30:33]
	ds_read_b64_tr_b16 v[188:189], v231 offset:1024
	ds_read_b64_tr_b16 v[190:191], v231 offset:5120
	s_waitcnt lgkmcnt(6)
	v_mfma_f32_16x16x32_bf16 v[26:29], v[192:195], v[168:171], v[26:29]
	v_mfma_f32_16x16x32_bf16 v[30:33], v[192:195], v[176:179], v[30:33]
	ds_read_b64_tr_b16 v[192:193], v231 offset:9216
	ds_read_b64_tr_b16 v[194:195], v231 offset:13312
	s_waitcnt lgkmcnt(6)
	v_mfma_f32_16x16x32_bf16 v[34:37], v[180:183], v[164:167], v[34:37]
	v_mfma_f32_16x16x32_bf16 v[38:41], v[180:183], v[172:175], v[38:41]
	ds_read_b64_tr_b16 v[180:181], v230 offset:1536
	ds_read_b64_tr_b16 v[182:183], v230 offset:5632
	s_waitcnt lgkmcnt(6)
	v_mfma_f32_16x16x32_bf16 v[34:37], v[184:187], v[168:171], v[34:37]
	v_mfma_f32_16x16x32_bf16 v[38:41], v[184:187], v[176:179], v[38:41]
	ds_read_b64_tr_b16 v[184:185], v230 offset:9728
	ds_read_b64_tr_b16 v[186:187], v230 offset:13824
	s_waitcnt lgkmcnt(6)
	v_mfma_f32_16x16x32_bf16 v[42:45], v[188:191], v[164:167], v[42:45]
	v_mfma_f32_16x16x32_bf16 v[46:49], v[188:191], v[172:175], v[46:49]
	ds_read_b64_tr_b16 v[188:189], v231 offset:1536
	ds_read_b64_tr_b16 v[190:191], v231 offset:5632
	s_waitcnt lgkmcnt(6)
	v_mfma_f32_16x16x32_bf16 v[42:45], v[192:195], v[168:171], v[42:45]
	v_mfma_f32_16x16x32_bf16 v[46:49], v[192:195], v[176:179], v[46:49]
	ds_read_b64_tr_b16 v[192:193], v231 offset:9728
	ds_read_b64_tr_b16 v[194:195], v231 offset:13824
	s_waitcnt lgkmcnt(6)
	v_mfma_f32_16x16x32_bf16 v[50:53], v[180:183], v[164:167], v[50:53]
	v_mfma_f32_16x16x32_bf16 v[54:57], v[180:183], v[172:175], v[54:57]
	s_waitcnt lgkmcnt(4)
	v_mfma_f32_16x16x32_bf16 v[50:53], v[184:187], v[168:171], v[50:53]
	v_mfma_f32_16x16x32_bf16 v[54:57], v[184:187], v[176:179], v[54:57]
	s_waitcnt lgkmcnt(2)
	v_mfma_f32_16x16x32_bf16 v[58:61], v[188:191], v[164:167], v[58:61]
	v_mfma_f32_16x16x32_bf16 v[62:65], v[188:191], v[172:175], v[62:65]
	s_waitcnt lgkmcnt(0)
	v_mfma_f32_16x16x32_bf16 v[58:61], v[192:195], v[168:171], v[58:61]
	v_mfma_f32_16x16x32_bf16 v[62:65], v[192:195], v[176:179], v[62:65]
	v_add_u32_e32 v230, s75, v226
	v_add_u32_e32 v231, s75, v227
	s_branch .Lm16_tile_end
; template <bool MLA> __device__ __forceinline__ void attn_unit(const AttnP& P, int b, int hh, int qb, LAS char* lds) {
;     ...
;     for (int t = 0; t < NT; ++t) {
;         const int buf = t & 1;
;         if (t + 1 < NT) LOADT(t + 1, buf ^ 1);
;         const int kb = kbase0 + 64 * t;
;         const bool act = (kb <= qlo + 31) && (MLA || kb + 63 >= qlo - (W - 1));
;         if (act) {
;             f32x16 p0 = f32x16{}, p1 = f32x16{};
;             if constexpr (MLA) {
; #pragma unroll
;                 for (int r = 0; r < 16; ++r) { p0[r] = -m_reg; p1[r] = -m_reg; } }
;             if constexpr (MLA) { qk_mla(p0, p1, (int)(uintptr_t)K_lds + buf * KBYTES, r32, hi, qr); }
;             else { qk64(p0, p1, K_lds + buf * KBYTES, r32, hi, qr); }
;             const int dq = qm - kb;
;             if constexpr (!MLA) {
; #pragma unroll
;                 for (int r = 0; r < 16; ++r) { const int c = (r & 3) + 8 * (r >> 2); p0[r] += bias_l[(dq - c) & 127]; p1[r] += bias_l[(dq - c - 32) & 127]; }
;             }
;             if (kb + 63 > qlo || (!MLA && kb <= qlo + 31 - W)) mask_tile(p0, p1, dq, (unsigned)W);
;             float mn, alpha; bf16x8 pa0, pa1, pa2, pa3;
;             if constexpr (MLA) { partialSM_pre(p0, p1, m_reg, alpha); (void)mn; } else { partialSM<SC9>(p0, p1, m_reg, mn, alpha); }
;             finishSM(p0, p1, alpha, l_reg, pa0, pa1, pa2, pa3);
;             if (__any(alpha < 1.f)) { if (hi == 0) al_l[r32] = alpha; asm volatile("s_waitcnt lgkmcnt(0)" ::: "memory");
; #pragma unroll
;                 for (int d_ = 0; d_ < NCB; ++d_)
; #pragma unroll
;                     for (int r = 0; r < 16; ++r) o[d_][r] *= al_l[crow(r, hi)]; }
;             SBAR();
;             pv_tile<NCB>(o, vb0 + buf * VBYTES, pa0, pa1, pa2, pa3);
;         }
;         if (t + 1 < NT) { asm volatile("s_waitcnt vmcnt(0)" ::: "memory"); WRITET(buf ^ 1); }
;         __syncthreads();
;     }
;     if (hi == 0) li_l[r32] = l_reg; asm volatile("s_waitcnt lgkmcnt(0)" ::: "memory");
;     bf16_t* Ow = (MLA ? P.QN + (rowbase + qlo) * 2048 + hh * 128 : P.QS + (rowbase + qlo) * 2048 + hh * 64);
; #pragma unroll
;     for (int r = 0; r < 16; ++r) { const int orow = crow(r, hi); const float rl = __builtin_amdgcn_rcpf(li_l[orow]);
; #pragma unroll
;         for (int d0 = 0; d0 < NCB; ++d0) { const float v = o[d0][r] * rl; const float vn = __shfl_xor(v, 1);
.Lm16_inact:
	s_add_u32 s36, s41, 1
	s_cmp_lt_u32 s36, s40
	s_cbranch_scc0 .Lm16_tile_end
	s_add_i32 s36, s5, s74
	s_mov_b32 m0, s36
	s_nop 0
	global_load_lds_dwordx4 v232, s[46:47]
	s_add_i32 m0, s36, 0x2000
	s_nop 0
	global_load_lds_dwordx4 v233, s[46:47]
	s_add_i32 m0, s36, 0x4000
	s_nop 0
	global_load_lds_dwordx4 v234, s[50:51]
	s_add_i32 s36, s5, s75
	s_mov_b32 m0, s36
	s_nop 0
	global_load_lds_dwordx4 v235, s[48:49]
	s_add_i32 m0, s36, 0x2000
	s_nop 0
	global_load_lds_dwordx4 v236, s[48:49]
	s_add_u32 s46, s46, 0x40000
	s_addc_u32 s47, s47, 0
	s_add_u32 s48, s48, 0x40000
	s_addc_u32 s49, s49, 0
	s_add_u32 s50, s50, 0x2000
	s_addc_u32 s51, s51, 0
.Lm16_tile_end:
	s_add_u32 s41, s41, 1
	s_add_u32 s42, s42, 64
	s_mov_b32 s36, s70
	s_mov_b32 s70, s74
	s_mov_b32 s74, s36
	s_mov_b32 s36, s71
	s_mov_b32 s71, s75
	s_mov_b32 s75, s36
	s_cmp_lt_u32 s41, s40
	s_waitcnt vmcnt(0) lgkmcnt(0)
	s_barrier
	s_cbranch_scc1 .Lm16_tile
	s_nop 7
	ds_bpermute_b32 v221, v246, v216
	s_waitcnt lgkmcnt(0)
	v_add_f32_e32 v216, v216, v221
	ds_bpermute_b32 v221, v247, v216
	s_waitcnt lgkmcnt(0)
	v_add_f32_e32 v216, v216, v221
	v_rcp_f32_e32 v216, v216
	ds_bpermute_b32 v221, v246, v217
	s_waitcnt lgkmcnt(0)
	v_add_f32_e32 v217, v217, v221
	ds_bpermute_b32 v221, v247, v217
	s_waitcnt lgkmcnt(0)
	v_add_f32_e32 v217, v217, v221
	v_rcp_f32_e32 v217, v217
	s_nop 0
	v_mul_f32_e32 v2, v2, v216
	v_mul_f32_e32 v3, v3, v216
	v_mul_f32_e32 v4, v4, v216
	v_mul_f32_e32 v5, v5, v216
	v_cvt_pk_bf16_f32 v2, v2, v3
	v_cvt_pk_bf16_f32 v3, v4, v5
	global_store_dwordx2 v241, v[2:3], s[66:67] offset:0
	v_mul_f32_e32 v6, v6, v217
	v_mul_f32_e32 v7, v7, v217
	v_mul_f32_e32 v8, v8, v217
	v_mul_f32_e32 v9, v9, v217
	v_cvt_pk_bf16_f32 v6, v6, v7
	v_cvt_pk_bf16_f32 v7, v8, v9
	global_store_dwordx2 v242, v[6:7], s[66:67] offset:0
	v_mul_f32_e32 v10, v10, v216
	v_mul_f32_e32 v11, v11, v216
	v_mul_f32_e32 v12, v12, v216
	v_mul_f32_e32 v13, v13, v216
	v_cvt_pk_bf16_f32 v10, v10, v11
	v_cvt_pk_bf16_f32 v11, v12, v13
	global_store_dwordx2 v241, v[10:11], s[66:67] offset:32
	v_mul_f32_e32 v14, v14, v217
	v_mul_f32_e32 v15, v15, v217
	v_mul_f32_e32 v16, v16, v217
	v_mul_f32_e32 v17, v17, v217
	v_cvt_pk_bf16_f32 v14, v14, v15
	v_cvt_pk_bf16_f32 v15, v16, v17
	global_store_dwordx2 v242, v[14:15], s[66:67] offset:32
	v_mul_f32_e32 v18, v18, v216
	v_mul_f32_e32 v19, v19, v216
	v_mul_f32_e32 v20, v20, v216
	v_mul_f32_e32 v21, v21, v216
	v_cvt_pk_bf16_f32 v18, v18, v19
	v_cvt_pk_bf16_f32 v19, v20, v21
	global_store_dwordx2 v241, v[18:19], s[66:67] offset:64
	v_mul_f32_e32 v22, v22, v217
	v_mul_f32_e32 v23, v23, v217
	v_mul_f32_e32 v24, v24, v217
	v_mul_f32_e32 v25, v25, v217
	v_cvt_pk_bf16_f32 v22, v22, v23
	v_cvt_pk_bf16_f32 v23, v24, v25
	global_store_dwordx2 v242, v[22:23], s[66:67] offset:64
	v_mul_f32_e32 v26, v26, v216
	v_mul_f32_e32 v27, v27, v216
	v_mul_f32_e32 v28, v28, v216
	v_mul_f32_e32 v29, v29, v216
	v_cvt_pk_bf16_f32 v26, v26, v27
	v_cvt_pk_bf16_f32 v27, v28, v29
	global_store_dwordx2 v241, v[26:27], s[66:67] offset:96
	v_mul_f32_e32 v30, v30, v217
	v_mul_f32_e32 v31, v31, v217
	v_mul_f32_e32 v32, v32, v217
	v_mul_f32_e32 v33, v33, v217
	v_cvt_pk_bf16_f32 v30, v30, v31
	v_cvt_pk_bf16_f32 v31, v32, v33
	global_store_dwordx2 v242, v[30:31], s[66:67] offset:96
	v_mul_f32_e32 v34, v34, v216
	v_mul_f32_e32 v35, v35, v216
	v_mul_f32_e32 v36, v36, v216
	v_mul_f32_e32 v37, v37, v216
	v_cvt_pk_bf16_f32 v34, v34, v35
	v_cvt_pk_bf16_f32 v35, v36, v37
	global_store_dwordx2 v241, v[34:35], s[66:67] offset:128
	v_mul_f32_e32 v38, v38, v217
	v_mul_f32_e32 v39, v39, v217
	v_mul_f32_e32 v40, v40, v217
	v_mul_f32_e32 v41, v41, v217
	v_cvt_pk_bf16_f32 v38, v38, v39
	v_cvt_pk_bf16_f32 v39, v40, v41
	global_store_dwordx2 v242, v[38:39], s[66:67] offset:128
	v_mul_f32_e32 v42, v42, v216
	v_mul_f32_e32 v43, v43, v216
	v_mul_f32_e32 v44, v44, v216
	v_mul_f32_e32 v45, v45, v216
	v_cvt_pk_bf16_f32 v42, v42, v43
	v_cvt_pk_bf16_f32 v43, v44, v45
	global_store_dwordx2 v241, v[42:43], s[66:67] offset:160
	v_mul_f32_e32 v46, v46, v217
	v_mul_f32_e32 v47, v47, v217
	v_mul_f32_e32 v48, v48, v217
	v_mul_f32_e32 v49, v49, v217
	v_cvt_pk_bf16_f32 v46, v46, v47
	v_cvt_pk_bf16_f32 v47, v48, v49
	global_store_dwordx2 v242, v[46:47], s[66:67] offset:160
	v_mul_f32_e32 v50, v50, v216
	v_mul_f32_e32 v51, v51, v216
	v_mul_f32_e32 v52, v52, v216
	v_mul_f32_e32 v53, v53, v216
	v_cvt_pk_bf16_f32 v50, v50, v51
	v_cvt_pk_bf16_f32 v51, v52, v53
	global_store_dwordx2 v241, v[50:51], s[66:67] offset:192
	v_mul_f32_e32 v54, v54, v217
	v_mul_f32_e32 v55, v55, v217
	v_mul_f32_e32 v56, v56, v217
	v_mul_f32_e32 v57, v57, v217
	v_cvt_pk_bf16_f32 v54, v54, v55
	v_cvt_pk_bf16_f32 v55, v56, v57
	global_store_dwordx2 v242, v[54:55], s[66:67] offset:192
	v_mul_f32_e32 v58, v58, v216
	v_mul_f32_e32 v59, v59, v216
	v_mul_f32_e32 v60, v60, v216
	v_mul_f32_e32 v61, v61, v216
	v_cvt_pk_bf16_f32 v58, v58, v59
	v_cvt_pk_bf16_f32 v59, v60, v61
	global_store_dwordx2 v241, v[58:59], s[66:67] offset:224
	v_mul_f32_e32 v62, v62, v217
	v_mul_f32_e32 v63, v63, v217
	v_mul_f32_e32 v64, v64, v217
	v_mul_f32_e32 v65, v65, v217
	v_cvt_pk_bf16_f32 v62, v62, v63
	v_cvt_pk_bf16_f32 v63, v64, v65
	global_store_dwordx2 v242, v[62:63], s[66:67] offset:224
	s_add_u32 s29, s29, 1
	s_cmp_lt_u32 s29, 2
	s_cbranch_scc1 .Lm16_unit
	s_add_u32 s28, s28, s3
	s_cmp_lt_u32 s28, 0x400
	s_cbranch_scc1 .Lm16_item
	s_waitcnt vmcnt(0) lgkmcnt(0)
